# grid barrier: acquire-side L1 invalidate issued at arrival (overlaps the wait) and leader post-release waits dropped; G6 final-pass ss loads hoisted
# speedup vs baseline: 1.0131x; 1.0130x over previous
; __device__ __forceinline__ unsigned xb_ld(unsigned* p)              { return __hip_atomic_load(p, __ATOMIC_RELAXED, __HIP_MEMORY_SCOPE_AGENT); }
; __device__ __forceinline__ unsigned xb_add(unsigned* p, unsigned v) { return __hip_atomic_fetch_add(p, v, __ATOMIC_RELAXED, __HIP_MEMORY_SCOPE_AGENT); }
; #define XB_SPIN(cond, bar) do { unsigned _sp = 0; while (cond) { __builtin_amdgcn_s_sleep(1); \
;     if ((++_sp & 255u) == 0u) { if (xb_ld(&(bar)[XB_TMO])) break; if (_sp > XB_SPIN_CAP) { atomicAdd(&(bar)[XB_TMO], 1u); break; } } } } while (0)
; __device__ __forceinline__ void xcd_barrier(const XcdBarrier& b) {
;     ...
;         __builtin_amdgcn_s_waitcnt(0);
;         unsigned nloc = b.st[0], nx = b.st[1];
;         if (nloc == 0u) { xcd_barrier_complete(bar, b.x, nloc, nx); b.st[0] = nloc; b.st[1] = nx; }
;         const unsigned old = xb_add(&bar[XB_XSUB(b.x)], 1u);
;         const unsigned gen = old / nloc;
;         if (old + 1u == (gen + 1u) * nloc) {
;             __builtin_amdgcn_fence(__ATOMIC_RELEASE, "agent");
;             asm volatile("s_waitcnt vmcnt(0)" ::: "memory");
;             const unsigned og = xb_add(&bar[XB_TOP], 1u);
;             const unsigned tg = og / nx;
;             if (og + 1u == (tg + 1u) * nx) xb_add(&bar[XB_TOPGEN], 1u);
;             else XB_SPIN(xb_ld(&bar[XB_TOPGEN]) == tg, bar);
;             __builtin_amdgcn_fence(__ATOMIC_ACQUIRE, "agent");
;             xb_add(&bar[XB_XGEN(b.x)], 1u);
;             asm volatile("s_waitcnt vmcnt(0)" ::: "memory");
;         } else {
;             XB_SPIN(xb_ld(&bar[XB_XGEN(b.x)]) == gen, bar);
;             __builtin_amdgcn_fence(__ATOMIC_ACQUIRE, "agent");
.LBB0_95:
	s_or_b64 exec, exec, s[12:13]
	v_cvt_f32_u32_e32 v4, v2
	s_waitcnt vmcnt(0)
	v_readfirstlane_b32 s10, v3
	v_sub_u32_e32 v3, 0, v2
	v_rcp_iflag_f32_e32 v4, v4
	v_add_u32_e32 v5, s10, v1
	v_mul_f32_e32 v4, 0x4f7ffffe, v4
	v_cvt_u32_f32_e32 v4, v4
	v_mul_lo_u32 v1, v3, v4
	v_mul_hi_u32 v1, v4, v1
	v_add_u32_e32 v1, v4, v1
	v_mul_hi_u32 v1, v5, v1
	v_mul_lo_u32 v3, v1, v2
	v_sub_u32_e32 v3, v5, v3
	v_add_u32_e32 v4, 1, v1
	v_cmp_ge_u32_e32 vcc, v3, v2
	s_nop 1
	v_cndmask_b32_e32 v1, v1, v4, vcc
	v_sub_u32_e32 v4, v3, v2
	v_cndmask_b32_e32 v3, v3, v4, vcc
	v_add_u32_e32 v4, 1, v1
	v_cmp_ge_u32_e32 vcc, v3, v2
	v_add_u32_e32 v3, 1, v5
	s_nop 0
	v_cndmask_b32_e32 v1, v1, v4, vcc
	v_mul_lo_u32 v4, v2, v1
	v_add_u32_e32 v2, v4, v2
	v_cmp_ne_u32_e32 vcc, v3, v2
	s_and_saveexec_b64 s[10:11], vcc
	s_xor_b64 s[10:11], exec, s[10:11]
	s_cbranch_execz .LBB0_109
	buffer_inv sc1
	s_waitcnt lgkmcnt(0)
	v_mov_b32_e32 v0, 0x2000
	global_load_dword v0, v0, s[8:9] offset:1024 sc1
	s_add_u32 s16, s8, 0x2400
	s_addc_u32 s17, s9, 0
	s_waitcnt vmcnt(0)
	v_cmp_eq_u32_e32 vcc, v0, v1
	s_and_saveexec_b64 s[12:13], vcc
	s_cbranch_execz .LBB0_108
	s_add_u32 s14, s92, 0x80200
	s_addc_u32 s15, s93, 0
	s_mov_b32 s28, 1
	s_mov_b64 s[18:19], 0
	v_mov_b32_e32 v0, 0
	s_branch .LBB0_99

; __device__ __forceinline__ unsigned xb_ld(unsigned* p)              { return __hip_atomic_load(p, __ATOMIC_RELAXED, __HIP_MEMORY_SCOPE_AGENT); }
; __device__ __forceinline__ unsigned xb_add(unsigned* p, unsigned v) { return __hip_atomic_fetch_add(p, v, __ATOMIC_RELAXED, __HIP_MEMORY_SCOPE_AGENT); }
; #define XB_SPIN(cond, bar) do { unsigned _sp = 0; while (cond) { __builtin_amdgcn_s_sleep(1); \
;     if ((++_sp & 255u) == 0u) { if (xb_ld(&(bar)[XB_TMO])) break; if (_sp > XB_SPIN_CAP) { atomicAdd(&(bar)[XB_TMO], 1u); break; } } } } while (0)
; __device__ __forceinline__ void xcd_barrier(const XcdBarrier& b) {
;     ...
;             __builtin_amdgcn_fence(__ATOMIC_ACQUIRE, "agent");
;             xb_add(&bar[XB_XGEN(b.x)], 1u);
;             asm volatile("s_waitcnt vmcnt(0)" ::: "memory");
;         } else {
;             XB_SPIN(xb_ld(&bar[XB_XGEN(b.x)]) == gen, bar);
;             __builtin_amdgcn_fence(__ATOMIC_ACQUIRE, "agent");
;             asm volatile("s_waitcnt vmcnt(0)" ::: "memory");
.LBB0_108:
	s_or_b64 exec, exec, s[12:13]
	s_waitcnt vmcnt(0)
	s_nop 0
	s_waitcnt vmcnt(0)
.LBB0_109:
	s_andn2_saveexec_b64 s[10:11], s[10:11]
	s_cbranch_execz .LBB0_129
	s_mov_b64 s[10:11], exec
	buffer_wbl2 sc1
	s_waitcnt lgkmcnt(0)
	s_waitcnt vmcnt(0)
	buffer_inv sc1
	v_mbcnt_lo_u32_b32 v1, s10, 0
	v_mbcnt_hi_u32_b32 v1, s11, v1
	v_cmp_eq_u32_e32 vcc, 0, v1
	s_and_saveexec_b64 s[12:13], vcc
	s_cbranch_execz .LBB0_112
	s_bcnt1_i32_b64 s10, s[10:11]
	v_mov_b32_e32 v2, 0x83000
	v_mov_b32_e32 v3, s10
	global_atomic_add v2, v2, v3, s[92:93] offset:1024 sc0

; __device__ __forceinline__ unsigned xb_ld(unsigned* p)              { return __hip_atomic_load(p, __ATOMIC_RELAXED, __HIP_MEMORY_SCOPE_AGENT); }
; __device__ __forceinline__ unsigned xb_add(unsigned* p, unsigned v) { return __hip_atomic_fetch_add(p, v, __ATOMIC_RELAXED, __HIP_MEMORY_SCOPE_AGENT); }
; #define XB_SPIN(cond, bar) do { unsigned _sp = 0; while (cond) { __builtin_amdgcn_s_sleep(1); \
;     if ((++_sp & 255u) == 0u) { if (xb_ld(&(bar)[XB_TMO])) break; if (_sp > XB_SPIN_CAP) { atomicAdd(&(bar)[XB_TMO], 1u); break; } } } } while (0)
; __device__ __forceinline__ void xcd_barrier(const XcdBarrier& b) {
;     ...
;             const unsigned og = xb_add(&bar[XB_TOP], 1u);
;             const unsigned tg = og / nx;
;             if (og + 1u == (tg + 1u) * nx) xb_add(&bar[XB_TOPGEN], 1u);
;             else XB_SPIN(xb_ld(&bar[XB_TOPGEN]) == tg, bar);
;             __builtin_amdgcn_fence(__ATOMIC_ACQUIRE, "agent");
;             xb_add(&bar[XB_XGEN(b.x)], 1u);
;             asm volatile("s_waitcnt vmcnt(0)" ::: "memory");
.LBB0_126:
	s_or_b64 exec, exec, s[10:11]
	s_mov_b64 s[10:11], exec
	v_mbcnt_lo_u32_b32 v0, s10, 0
	v_mbcnt_hi_u32_b32 v0, s11, v0
	v_cmp_eq_u32_e32 vcc, 0, v0
	s_nop 0
	s_nop 0
	s_and_saveexec_b64 s[12:13], vcc
	s_cbranch_execz .LBB0_128
	s_bcnt1_i32_b64 s10, s[10:11]
	v_mov_b32_e32 v0, 0x2000
	v_mov_b32_e32 v1, s10
	global_atomic_add v0, v1, s[8:9] offset:1024
.LBB0_128:
	s_or_b64 exec, exec, s[12:13]
	s_nop 0

;     __device__ __forceinline__ void operator()(const f32x4 (&acc_)[2][2][4][2], const Unit& u, int wr, int wc, int fr, int fq) const {
;     ...
;         __builtin_amdgcn_s_barrier(); asm volatile("" ::: "memory");
;         f32x4 gv[2][2];
; #pragma unroll
;         for (int bj = 0; bj < 2; ++bj)
; #pragma unroll
;             for (int n = 0; n < 2; ++n) gv[bj][n] = *(const f32x4*)(fn + col0 + bj * 128 + n * 16);
; #pragma unroll
;         for (int ai = 0; ai < 2; ++ai)
; #pragma unroll
;             for (int m = 0; m < 4; ++m) { const int row = row0 + ai * 128 + m * 16;
;                 const float rs = rsqrtf(__hip_atomic_load(ss + row, __ATOMIC_RELAXED, __HIP_MEMORY_SCOPE_AGENT) * (1.0f / D) + EPS);
; #pragma unroll
;                 for (int bj = 0; bj < 2; ++bj)
; #pragma unroll
;                     for (int n = 0; n < 2; ++n) *(f32x4*)(out + (size_t)row * D + col0 + bj * 128 + n * 16) = acc[ai][bj][m][n] * rs * gv[bj][n]; }
.LBB0_1428:
	s_or_b64 exec, exec, s[6:7]
	v_lshlrev_b64 v[64:65], 2, v[202:203]
	s_barrier
	s_waitcnt lgkmcnt(0)
	v_lshl_add_u64 v[0:1], s[8:9], 0, v[64:65]
	global_load_dwordx4 v[12:15], v[0:1], off
	global_load_dwordx4 v[8:11], v[0:1], off offset:64
	global_load_dwordx4 v[4:7], v[0:1], off offset:512
	s_nop 0
	global_load_dwordx4 v[0:3], v[0:1], off offset:576
	s_nop 0
	global_load_dword v216, v[112:113], off sc1
	global_load_dword v217, v[112:113], off offset:64 sc1
	global_load_dword v218, v[112:113], off offset:128 sc1
	global_load_dword v219, v[112:113], off offset:192 sc1
	global_load_dword v220, v[112:113], off offset:512 sc1
	global_load_dword v221, v[112:113], off offset:576 sc1
	global_load_dword v222, v[112:113], off offset:640 sc1
	global_load_dword v223, v[112:113], off offset:704 sc1
	s_nop 0
	v_lshl_add_u64 v[78:79], v[198:199], 2, s[16:17]
	s_waitcnt vmcnt(7)
	v_fmamk_f32 v66, v216, 0x3a800000, v225
	v_mul_f32_e32 v67, 0x4b800000, v66
	v_cmp_gt_f32_e32 vcc, s57, v66
	s_nop 1
	v_cndmask_b32_e32 v66, v66, v67, vcc
	v_rsq_f32_e32 v68, v66
	v_lshl_add_u64 v[66:67], s[10:11], 0, v[200:201]
	v_lshl_add_u64 v[86:87], v[66:67], 0, v[64:65]
	v_mul_f32_e32 v66, 0x45800000, v68
	v_cndmask_b32_e32 v66, v68, v66, vcc
	v_pk_mul_f32 v[70:71], v[124:125], v[66:67] op_sel_hi:[1,0]
	v_pk_mul_f32 v[68:69], v[126:127], v[66:67] op_sel_hi:[1,0]
	v_pk_mul_f32 v[74:75], v[206:207], v[66:67] op_sel_hi:[1,0]
	v_pk_mul_f32 v[72:73], v[204:205], v[66:67] op_sel_hi:[1,0]
	v_pk_mul_f32 v[90:91], v[210:211], v[66:67] op_sel_hi:[1,0]
	v_pk_mul_f32 v[76:77], v[208:209], v[66:67] op_sel_hi:[1,0]
	v_pk_mul_f32 v[94:95], v[214:215], v[66:67] op_sel_hi:[1,0]
	v_pk_mul_f32 v[92:93], v[212:213], v[66:67] op_sel_hi:[1,0]
	v_pk_mul_f32 v[68:69], v[14:15], v[68:69]
	v_pk_mul_f32 v[66:67], v[12:13], v[70:71]
	v_pk_mul_f32 v[72:73], v[10:11], v[72:73]
	v_pk_mul_f32 v[70:71], v[8:9], v[74:75]
	v_pk_mul_f32 v[76:77], v[6:7], v[76:77]
	v_pk_mul_f32 v[74:75], v[4:5], v[90:91]
	v_pk_mul_f32 v[92:93], v[2:3], v[92:93]
	v_pk_mul_f32 v[90:91], v[0:1], v[94:95]
	global_store_dwordx4 v[86:87], v[66:69], off
	global_store_dwordx4 v[86:87], v[70:73], off offset:64
	global_store_dwordx4 v[86:87], v[74:77], off offset:512
	global_store_dwordx4 v[86:87], v[90:93], off offset:576
	s_nop 0
	v_lshl_add_u64 v[78:79], v[194:195], 2, s[16:17]
	s_waitcnt vmcnt(10)
	v_fmamk_f32 v66, v217, 0x3a800000, v225
	v_mul_f32_e32 v67, 0x4b800000, v66
	v_cmp_gt_f32_e32 vcc, s57, v66
	s_nop 1
	v_cndmask_b32_e32 v66, v66, v67, vcc
	v_rsq_f32_e32 v68, v66
	v_lshl_add_u64 v[66:67], s[10:11], 0, v[196:197]
	v_lshl_add_u64 v[86:87], v[66:67], 0, v[64:65]
	v_mul_f32_e32 v66, 0x45800000, v68
	v_cndmask_b32_e32 v66, v68, v66, vcc
	v_pk_mul_f32 v[70:71], v[172:173], v[66:67] op_sel_hi:[1,0]
	v_pk_mul_f32 v[68:69], v[174:175], v[66:67] op_sel_hi:[1,0]
	v_pk_mul_f32 v[74:75], v[168:169], v[66:67] op_sel_hi:[1,0]
	v_pk_mul_f32 v[72:73], v[170:171], v[66:67] op_sel_hi:[1,0]
	v_pk_mul_f32 v[90:91], v[164:165], v[66:67] op_sel_hi:[1,0]
	v_pk_mul_f32 v[76:77], v[166:167], v[66:67] op_sel_hi:[1,0]
	v_pk_mul_f32 v[94:95], v[160:161], v[66:67] op_sel_hi:[1,0]
	v_pk_mul_f32 v[92:93], v[162:163], v[66:67] op_sel_hi:[1,0]
	v_pk_mul_f32 v[68:69], v[14:15], v[68:69]
	v_pk_mul_f32 v[66:67], v[12:13], v[70:71]
	v_pk_mul_f32 v[72:73], v[10:11], v[72:73]
	v_pk_mul_f32 v[70:71], v[8:9], v[74:75]
	v_pk_mul_f32 v[76:77], v[6:7], v[76:77]
	v_pk_mul_f32 v[74:75], v[4:5], v[90:91]
	v_pk_mul_f32 v[92:93], v[2:3], v[92:93]
	v_pk_mul_f32 v[90:91], v[0:1], v[94:95]
	global_store_dwordx4 v[86:87], v[66:69], off
	global_store_dwordx4 v[86:87], v[70:73], off offset:64
	global_store_dwordx4 v[86:87], v[74:77], off offset:512
	global_store_dwordx4 v[86:87], v[90:93], off offset:576
	s_nop 0
	v_lshl_add_u64 v[78:79], v[190:191], 2, s[16:17]
	s_waitcnt vmcnt(13)
	v_fmamk_f32 v66, v218, 0x3a800000, v225
	v_mul_f32_e32 v67, 0x4b800000, v66
	v_cmp_gt_f32_e32 vcc, s57, v66
	s_nop 1
	v_cndmask_b32_e32 v66, v66, v67, vcc
	v_rsq_f32_e32 v68, v66
	v_lshl_add_u64 v[66:67], s[10:11], 0, v[192:193]
	v_lshl_add_u64 v[86:87], v[66:67], 0, v[64:65]
	v_mul_f32_e32 v66, 0x45800000, v68
	v_cndmask_b32_e32 v66, v68, v66, vcc
	v_pk_mul_f32 v[70:71], v[122:123], v[66:67] op_sel_hi:[1,0]
	v_pk_mul_f32 v[68:69], v[120:121], v[66:67] op_sel_hi:[1,0]
	v_pk_mul_f32 v[74:75], v[152:153], v[66:67] op_sel_hi:[1,0]
	v_pk_mul_f32 v[72:73], v[154:155], v[66:67] op_sel_hi:[1,0]
	v_pk_mul_f32 v[90:91], v[148:149], v[66:67] op_sel_hi:[1,0]
	v_pk_mul_f32 v[76:77], v[150:151], v[66:67] op_sel_hi:[1,0]
	v_pk_mul_f32 v[94:95], v[144:145], v[66:67] op_sel_hi:[1,0]
	v_pk_mul_f32 v[92:93], v[146:147], v[66:67] op_sel_hi:[1,0]
	v_pk_mul_f32 v[68:69], v[14:15], v[68:69]
	v_pk_mul_f32 v[66:67], v[12:13], v[70:71]
	v_pk_mul_f32 v[72:73], v[10:11], v[72:73]
	v_pk_mul_f32 v[70:71], v[8:9], v[74:75]
	v_pk_mul_f32 v[76:77], v[6:7], v[76:77]
	v_pk_mul_f32 v[74:75], v[4:5], v[90:91]
	v_pk_mul_f32 v[92:93], v[2:3], v[92:93]
	v_pk_mul_f32 v[90:91], v[0:1], v[94:95]
	global_store_dwordx4 v[86:87], v[66:69], off
	global_store_dwordx4 v[86:87], v[70:73], off offset:64
	global_store_dwordx4 v[86:87], v[74:77], off offset:512
	global_store_dwordx4 v[86:87], v[90:93], off offset:576
	s_nop 0
	s_waitcnt vmcnt(16)
;     __device__ __forceinline__ void operator()(const f32x4 (&acc_)[2][2][4][2], const Unit& u, int wr, int wc, int fr, int fq) const {
;     ...
;         for (int ai = 0; ai < 2; ++ai)
; #pragma unroll
;             for (int m = 0; m < 4; ++m) { const int row = row0 + ai * 128 + m * 16;
;                 const float rs = rsqrtf(__hip_atomic_load(ss + row, __ATOMIC_RELAXED, __HIP_MEMORY_SCOPE_AGENT) * (1.0f / D) + EPS);
; #pragma unroll
;                 for (int bj = 0; bj < 2; ++bj)
; #pragma unroll
;                     for (int n = 0; n < 2; ++n) *(f32x4*)(out + (size_t)row * D + col0 + bj * 128 + n * 16) = acc[ai][bj][m][n] * rs * gv[bj][n]; }
	v_fmamk_f32 v66, v219, 0x3a800000, v225
	v_mul_f32_e32 v67, 0x4b800000, v66
	v_cmp_gt_f32_e32 vcc, s57, v66
	s_nop 1
	v_cndmask_b32_e32 v66, v66, v67, vcc
	v_rsq_f32_e32 v68, v66
	v_lshl_add_u64 v[66:67], s[10:11], 0, v[188:189]
	v_lshl_add_u64 v[78:79], v[66:67], 0, v[64:65]
	v_mul_f32_e32 v66, 0x45800000, v68
	v_cndmask_b32_e32 v66, v68, v66, vcc
	v_pk_mul_f32 v[70:71], v[140:141], v[66:67] op_sel_hi:[1,0]
	v_pk_mul_f32 v[68:69], v[142:143], v[66:67] op_sel_hi:[1,0]
	v_pk_mul_f32 v[74:75], v[136:137], v[66:67] op_sel_hi:[1,0]
	v_pk_mul_f32 v[72:73], v[138:139], v[66:67] op_sel_hi:[1,0]
	v_pk_mul_f32 v[86:87], v[132:133], v[66:67] op_sel_hi:[1,0]
	v_pk_mul_f32 v[76:77], v[134:135], v[66:67] op_sel_hi:[1,0]
	v_pk_mul_f32 v[90:91], v[156:157], v[66:67] op_sel_hi:[1,0]
	v_pk_mul_f32 v[92:93], v[130:131], v[66:67] op_sel_hi:[1,0]
	v_pk_mul_f32 v[68:69], v[14:15], v[68:69]
	v_pk_mul_f32 v[66:67], v[12:13], v[70:71]
	v_pk_mul_f32 v[72:73], v[10:11], v[72:73]
	v_pk_mul_f32 v[70:71], v[8:9], v[74:75]
	v_pk_mul_f32 v[76:77], v[6:7], v[76:77]
	v_pk_mul_f32 v[74:75], v[4:5], v[86:87]
	v_pk_mul_f32 v[92:93], v[2:3], v[92:93]
	v_pk_mul_f32 v[90:91], v[0:1], v[90:91]
	global_store_dwordx4 v[78:79], v[66:69], off
	global_store_dwordx4 v[78:79], v[70:73], off offset:64
	global_store_dwordx4 v[78:79], v[74:77], off offset:512
	global_store_dwordx4 v[78:79], v[90:93], off offset:576
	s_nop 0
	s_waitcnt vmcnt(19)
	v_fmamk_f32 v66, v220, 0x3a800000, v225
	v_mul_f32_e32 v67, 0x4b800000, v66
	v_cmp_gt_f32_e32 vcc, s57, v66
	s_nop 1
	v_cndmask_b32_e32 v66, v66, v67, vcc
	v_rsq_f32_e32 v68, v66
	v_lshl_add_u64 v[66:67], s[10:11], 0, v[128:129]
	v_lshl_add_u64 v[66:67], v[66:67], 0, v[64:65]
	v_mul_f32_e32 v69, 0x45800000, v68
	v_cndmask_b32_e32 v68, v68, v69, vcc
	v_pk_mul_f32 v[60:61], v[60:61], v[68:69] op_sel_hi:[1,0]
	v_pk_mul_f32 v[62:63], v[62:63], v[68:69] op_sel_hi:[1,0]
	v_pk_mul_f32 v[56:57], v[56:57], v[68:69] op_sel_hi:[1,0]
	v_pk_mul_f32 v[58:59], v[58:59], v[68:69] op_sel_hi:[1,0]
	v_pk_mul_f32 v[70:71], v[52:53], v[68:69] op_sel_hi:[1,0]
	v_pk_mul_f32 v[72:73], v[54:55], v[68:69] op_sel_hi:[1,0]
	v_pk_mul_f32 v[74:75], v[48:49], v[68:69] op_sel_hi:[1,0]
	v_pk_mul_f32 v[68:69], v[50:51], v[68:69] op_sel_hi:[1,0]
	v_pk_mul_f32 v[50:51], v[14:15], v[62:63]
	v_pk_mul_f32 v[48:49], v[12:13], v[60:61]
	v_pk_mul_f32 v[54:55], v[10:11], v[58:59]
	v_pk_mul_f32 v[52:53], v[8:9], v[56:57]
	v_pk_mul_f32 v[58:59], v[6:7], v[72:73]
	v_pk_mul_f32 v[56:57], v[4:5], v[70:71]
	v_pk_mul_f32 v[62:63], v[2:3], v[68:69]
	v_pk_mul_f32 v[60:61], v[0:1], v[74:75]
	global_store_dwordx4 v[66:67], v[48:51], off
	global_store_dwordx4 v[66:67], v[52:55], off offset:64
	global_store_dwordx4 v[66:67], v[56:59], off offset:512
	global_store_dwordx4 v[66:67], v[60:63], off offset:576
	s_nop 0
	s_waitcnt vmcnt(22)
	v_fmamk_f32 v48, v221, 0x3a800000, v225
	v_mul_f32_e32 v49, 0x4b800000, v48
	v_cmp_gt_f32_e32 vcc, s57, v48
	s_nop 1
	v_cndmask_b32_e32 v48, v48, v49, vcc
	v_rsq_f32_e32 v50, v48
	v_lshl_add_u64 v[48:49], s[10:11], 0, v[118:119]
	v_lshl_add_u64 v[56:57], v[48:49], 0, v[64:65]
	v_mul_f32_e32 v48, 0x45800000, v50
	v_cndmask_b32_e32 v48, v50, v48, vcc
	v_pk_mul_f32 v[44:45], v[44:45], v[48:49] op_sel_hi:[1,0]
	v_pk_mul_f32 v[46:47], v[46:47], v[48:49] op_sel_hi:[1,0]
	v_pk_mul_f32 v[50:51], v[104:105], v[48:49] op_sel_hi:[1,0]
	v_pk_mul_f32 v[52:53], v[42:43], v[48:49] op_sel_hi:[1,0]
	v_pk_mul_f32 v[54:55], v[100:101], v[48:49] op_sel_hi:[1,0]
	v_pk_mul_f32 v[58:59], v[40:41], v[48:49] op_sel_hi:[1,0]
	v_pk_mul_f32 v[60:61], v[96:97], v[48:49] op_sel_hi:[1,0]
	v_pk_mul_f32 v[62:63], v[98:99], v[48:49] op_sel_hi:[1,0]
	v_pk_mul_f32 v[42:43], v[14:15], v[46:47]
	v_pk_mul_f32 v[40:41], v[12:13], v[44:45]
	v_pk_mul_f32 v[46:47], v[10:11], v[52:53]
	v_pk_mul_f32 v[44:45], v[8:9], v[50:51]
	v_pk_mul_f32 v[50:51], v[6:7], v[58:59]
	v_pk_mul_f32 v[48:49], v[4:5], v[54:55]
	v_pk_mul_f32 v[54:55], v[2:3], v[62:63]
	v_pk_mul_f32 v[52:53], v[0:1], v[60:61]
	global_store_dwordx4 v[56:57], v[40:43], off
	global_store_dwordx4 v[56:57], v[44:47], off offset:64
	global_store_dwordx4 v[56:57], v[48:51], off offset:512
	global_store_dwordx4 v[56:57], v[52:55], off offset:576
	s_nop 0
	s_waitcnt vmcnt(25)
;     __device__ __forceinline__ void operator()(const f32x4 (&acc_)[2][2][4][2], const Unit& u, int wr, int wc, int fr, int fq) const {
;     ...
;         for (int ai = 0; ai < 2; ++ai)
; #pragma unroll
;             for (int m = 0; m < 4; ++m) { const int row = row0 + ai * 128 + m * 16;
;                 const float rs = rsqrtf(__hip_atomic_load(ss + row, __ATOMIC_RELAXED, __HIP_MEMORY_SCOPE_AGENT) * (1.0f / D) + EPS);
; #pragma unroll
;                 for (int bj = 0; bj < 2; ++bj)
; #pragma unroll
;                     for (int n = 0; n < 2; ++n) *(f32x4*)(out + (size_t)row * D + col0 + bj * 128 + n * 16) = acc[ai][bj][m][n] * rs * gv[bj][n]; }
	v_fmamk_f32 v40, v222, 0x3a800000, v225
	v_mul_f32_e32 v41, 0x4b800000, v40
	v_cmp_gt_f32_e32 vcc, s57, v40
	s_nop 1
	v_cndmask_b32_e32 v40, v40, v41, vcc
	v_rsq_f32_e32 v42, v40
	v_lshl_add_u64 v[40:41], s[10:11], 0, v[116:117]
	v_lshl_add_u64 v[48:49], v[40:41], 0, v[64:65]
	v_mul_f32_e32 v40, 0x45800000, v42
	v_cndmask_b32_e32 v40, v42, v40, vcc
	v_pk_mul_f32 v[32:33], v[32:33], v[40:41] op_sel_hi:[1,0]
	v_pk_mul_f32 v[34:35], v[34:35], v[40:41] op_sel_hi:[1,0]
	v_pk_mul_f32 v[42:43], v[88:89], v[40:41] op_sel_hi:[1,0]
	v_pk_mul_f32 v[36:37], v[36:37], v[40:41] op_sel_hi:[1,0]
	v_pk_mul_f32 v[44:45], v[84:85], v[40:41] op_sel_hi:[1,0]
	v_pk_mul_f32 v[46:47], v[38:39], v[40:41] op_sel_hi:[1,0]
	v_pk_mul_f32 v[50:51], v[80:81], v[40:41] op_sel_hi:[1,0]
	v_pk_mul_f32 v[52:53], v[82:83], v[40:41] op_sel_hi:[1,0]
	v_pk_mul_f32 v[34:35], v[14:15], v[34:35]
	v_pk_mul_f32 v[32:33], v[12:13], v[32:33]
	v_pk_mul_f32 v[38:39], v[10:11], v[36:37]
	v_pk_mul_f32 v[36:37], v[8:9], v[42:43]
	v_pk_mul_f32 v[42:43], v[6:7], v[46:47]
	v_pk_mul_f32 v[40:41], v[4:5], v[44:45]
	v_pk_mul_f32 v[46:47], v[2:3], v[52:53]
	v_pk_mul_f32 v[44:45], v[0:1], v[50:51]
	global_store_dwordx4 v[48:49], v[32:35], off
	global_store_dwordx4 v[48:49], v[36:39], off offset:64
	global_store_dwordx4 v[48:49], v[40:43], off offset:512
	global_store_dwordx4 v[48:49], v[44:47], off offset:576
	s_nop 0
	s_and_b64 vcc, exec, s[4:5]
	s_mov_b64 s[4:5], -1
	s_waitcnt vmcnt(28)
	v_fmamk_f32 v32, v223, 0x3a800000, v225
	v_mul_f32_e32 v33, 0x4b800000, v32
	v_cmp_gt_f32_e64 s[6:7], s57, v32
	s_nop 1
	v_cndmask_b32_e64 v32, v32, v33, s[6:7]
	v_rsq_f32_e32 v34, v32
	v_lshl_add_u64 v[32:33], s[10:11], 0, v[114:115]
	v_lshl_add_u64 v[32:33], v[32:33], 0, v[64:65]
	v_mul_f32_e32 v35, 0x45800000, v34
	v_cndmask_b32_e64 v34, v34, v35, s[6:7]
	v_pk_mul_f32 v[16:17], v[16:17], v[34:35] op_sel_hi:[1,0]
	v_pk_mul_f32 v[18:19], v[18:19], v[34:35] op_sel_hi:[1,0]
	v_pk_mul_f32 v[22:23], v[22:23], v[34:35] op_sel_hi:[1,0]
	v_pk_mul_f32 v[20:21], v[20:21], v[34:35] op_sel_hi:[1,0]
	v_pk_mul_f32 v[26:27], v[26:27], v[34:35] op_sel_hi:[1,0]
	v_pk_mul_f32 v[24:25], v[24:25], v[34:35] op_sel_hi:[1,0]
	v_pk_mul_f32 v[30:31], v[30:31], v[34:35] op_sel_hi:[1,0]
	v_pk_mul_f32 v[28:29], v[28:29], v[34:35] op_sel_hi:[1,0]
	v_pk_mul_f32 v[14:15], v[14:15], v[18:19]
	v_pk_mul_f32 v[12:13], v[12:13], v[16:17]
	v_pk_mul_f32 v[10:11], v[10:11], v[20:21]
	v_pk_mul_f32 v[8:9], v[8:9], v[22:23]
	v_pk_mul_f32 v[6:7], v[6:7], v[24:25]
	v_pk_mul_f32 v[4:5], v[4:5], v[26:27]
	v_pk_mul_f32 v[2:3], v[2:3], v[28:29]
	v_pk_mul_f32 v[0:1], v[0:1], v[30:31]
	global_store_dwordx4 v[32:33], v[12:15], off
	global_store_dwordx4 v[32:33], v[8:11], off offset:64
	global_store_dwordx4 v[32:33], v[4:7], off offset:512
	global_store_dwordx4 v[32:33], v[0:3], off offset:576
	s_cbranch_vccnz .LBB0_1383
	s_andn2_b64 vcc, exec, s[14:15]
	s_cbranch_vccnz .LBB0_1382
	s_barrier
	s_branch .LBB0_1382
